# RG-LRU pass 3 carry fold: double-buffered batches of 15 pairs, at most 60 loads outstanding
# speedup vs baseline: 1.0181x; 1.0003x over previous
; __device__ __forceinline__ void stage_lru3(const Params& P) {
;     ...
;         for (int it = gw; it < NCH * 8; it += ngw) {
;             const int c = it >> 3, h = it & 7, ch = h * 64 + lane;
;             const float* CHA = (const float*)(ws + OFF_CHA); const float* CHB = (const float*)(ws + OFF_CHB);
;             float hh = 0.f;
; #pragma unroll 1
;             for (int cb = 0; cb < c; cb += 16) {
;                 float ca[16], cbv[16];
; #pragma unroll
;                 for (int i = 0; i < 16; ++i) { const int cc = cb + i < c ? cb + i : c - 1; ca[i] = CHA[(size_t)cc * 512 + ch]; cbv[i] = CHB[(size_t)cc * 512 + ch]; }
; #pragma unroll
;                 for (int i = 0; i < 16; ++i) if (cb + i < c) hh = ca[i] * hh + cbv[i];
.LBB0_233:
	s_ashr_i32 s8, s2, 3
	s_cmp_lt_i32 s8, 1
	s_cbranch_scc1 .LBB0_237
	s_lshl_b32 s0, s2, 6
	s_and_b32 s0, s0, 0x1c0
	v_or_b32_e32 v0, s0, v8
	s_add_i32 s9, s8, -1
	v_mov_b32_e32 v6, 0
	s_mov_b32 s10, 0
	v_lshlrev_b32_e32 v0, 2, v0
	s_cmp_le_i32 s8, 14
	s_cbranch_scc1 .Lfp_done
	s_add_i32 s1, s10, 0
	s_lshl_b32 s1, s1, 11
	v_add_u32_e32 v198, s1, v0
	global_load_dword v64, v198, s[4:5]
	global_load_dword v128, v198, s[6:7]
	global_load_dword v65, v198, s[4:5] offset:2048
	global_load_dword v129, v198, s[6:7] offset:2048
	v_add_u32_e32 v200, 0x1000, v198
	global_load_dword v66, v200, s[4:5]
	global_load_dword v130, v200, s[6:7]
	global_load_dword v67, v200, s[4:5] offset:2048
	global_load_dword v131, v200, s[6:7] offset:2048
	v_add_u32_e32 v201, 0x2000, v198
	global_load_dword v68, v201, s[4:5]
	global_load_dword v132, v201, s[6:7]
	global_load_dword v69, v201, s[4:5] offset:2048
	global_load_dword v133, v201, s[6:7] offset:2048
	v_add_u32_e32 v199, 0x3000, v198
	global_load_dword v70, v199, s[4:5]
	global_load_dword v134, v199, s[6:7]
	global_load_dword v71, v199, s[4:5] offset:2048
	global_load_dword v135, v199, s[6:7] offset:2048
	v_add_u32_e32 v200, 0x4000, v198
	global_load_dword v72, v200, s[4:5]
	global_load_dword v136, v200, s[6:7]
	global_load_dword v73, v200, s[4:5] offset:2048
	global_load_dword v137, v200, s[6:7] offset:2048
	v_add_u32_e32 v201, 0x5000, v198
	global_load_dword v74, v201, s[4:5]
	global_load_dword v138, v201, s[6:7]
	global_load_dword v75, v201, s[4:5] offset:2048
	global_load_dword v139, v201, s[6:7] offset:2048
	v_add_u32_e32 v199, 0x6000, v198
	global_load_dword v76, v199, s[4:5]
	global_load_dword v140, v199, s[6:7]
	global_load_dword v77, v199, s[4:5] offset:2048
	global_load_dword v141, v199, s[6:7] offset:2048
	v_add_u32_e32 v200, 0x7000, v198
	global_load_dword v78, v200, s[4:5]
	global_load_dword v142, v200, s[6:7]
.Lfp_x:
	s_add_i32 s0, s10, 30
	s_cmp_le_i32 s0, s8
	s_cbranch_scc0 .Lfp_x_last
	s_add_i32 s1, s10, 15
	s_lshl_b32 s1, s1, 11
	v_add_u32_e32 v198, s1, v0
	global_load_dword v96, v198, s[4:5]
	global_load_dword v165, v198, s[6:7]
	global_load_dword v97, v198, s[4:5] offset:2048
	global_load_dword v167, v198, s[6:7] offset:2048
	v_add_u32_e32 v200, 0x1000, v198
	global_load_dword v98, v200, s[4:5]
	global_load_dword v168, v200, s[6:7]
	global_load_dword v99, v200, s[4:5] offset:2048
	global_load_dword v169, v200, s[6:7] offset:2048
	v_add_u32_e32 v201, 0x2000, v198
	global_load_dword v100, v201, s[4:5]
	global_load_dword v170, v201, s[6:7]
	global_load_dword v101, v201, s[4:5] offset:2048
	global_load_dword v171, v201, s[6:7] offset:2048
	v_add_u32_e32 v199, 0x3000, v198
	global_load_dword v102, v199, s[4:5]
	global_load_dword v172, v199, s[6:7]
	global_load_dword v103, v199, s[4:5] offset:2048
	global_load_dword v173, v199, s[6:7] offset:2048
	v_add_u32_e32 v200, 0x4000, v198
	global_load_dword v104, v200, s[4:5]
	global_load_dword v174, v200, s[6:7]
	global_load_dword v105, v200, s[4:5] offset:2048
	global_load_dword v175, v200, s[6:7] offset:2048
	v_add_u32_e32 v201, 0x5000, v198
	global_load_dword v106, v201, s[4:5]
	global_load_dword v176, v201, s[6:7]
	global_load_dword v107, v201, s[4:5] offset:2048
	global_load_dword v177, v201, s[6:7] offset:2048
	v_add_u32_e32 v199, 0x6000, v198
	global_load_dword v108, v199, s[4:5]
	global_load_dword v178, v199, s[6:7]
	global_load_dword v109, v199, s[4:5] offset:2048
	global_load_dword v179, v199, s[6:7] offset:2048
	v_add_u32_e32 v200, 0x7000, v198
	global_load_dword v110, v200, s[4:5]
	global_load_dword v180, v200, s[6:7]
	s_waitcnt vmcnt(30)
	v_fmac_f32_e32 v128, v6, v64
	v_fmac_f32_e32 v129, v128, v65
	v_fmac_f32_e32 v130, v129, v66
	v_fmac_f32_e32 v131, v130, v67
	v_fmac_f32_e32 v132, v131, v68
	v_fmac_f32_e32 v133, v132, v69
	v_fmac_f32_e32 v134, v133, v70
	v_fmac_f32_e32 v135, v134, v71
	v_fmac_f32_e32 v136, v135, v72
	v_fmac_f32_e32 v137, v136, v73
	v_fmac_f32_e32 v138, v137, v74
	v_fmac_f32_e32 v139, v138, v75
	v_fmac_f32_e32 v140, v139, v76
	v_fmac_f32_e32 v141, v140, v77
	v_fmac_f32_e32 v142, v141, v78
	v_mov_b32_e32 v6, v142
	s_add_i32 s10, s10, 15
	s_branch .Lfp_y
; __device__ __forceinline__ void stage_lru3(const Params& P) {
;     ...
;         for (int it = gw; it < NCH * 8; it += ngw) {
;             const int c = it >> 3, h = it & 7, ch = h * 64 + lane;
;             const float* CHA = (const float*)(ws + OFF_CHA); const float* CHB = (const float*)(ws + OFF_CHB);
;             float hh = 0.f;
; #pragma unroll 1
;             for (int cb = 0; cb < c; cb += 16) {
;                 float ca[16], cbv[16];
; #pragma unroll
;                 for (int i = 0; i < 16; ++i) { const int cc = cb + i < c ? cb + i : c - 1; ca[i] = CHA[(size_t)cc * 512 + ch]; cbv[i] = CHB[(size_t)cc * 512 + ch]; }
; #pragma unroll
;                 for (int i = 0; i < 16; ++i) if (cb + i < c) hh = ca[i] * hh + cbv[i];
.Lfp_x_last:
	s_waitcnt vmcnt(0)
	v_fmac_f32_e32 v128, v6, v64
	v_fmac_f32_e32 v129, v128, v65
	v_fmac_f32_e32 v130, v129, v66
	v_fmac_f32_e32 v131, v130, v67
	v_fmac_f32_e32 v132, v131, v68
	v_fmac_f32_e32 v133, v132, v69
	v_fmac_f32_e32 v134, v133, v70
	v_fmac_f32_e32 v135, v134, v71
	v_fmac_f32_e32 v136, v135, v72
	v_fmac_f32_e32 v137, v136, v73
	v_fmac_f32_e32 v138, v137, v74
	v_fmac_f32_e32 v139, v138, v75
	v_fmac_f32_e32 v140, v139, v76
	v_fmac_f32_e32 v141, v140, v77
	v_fmac_f32_e32 v142, v141, v78
	v_mov_b32_e32 v6, v142
	s_add_i32 s10, s10, 15
	s_branch .Lfp_done
.Lfp_y:
	s_add_i32 s0, s10, 30
	s_cmp_le_i32 s0, s8
	s_cbranch_scc0 .Lfp_y_last
	s_add_i32 s1, s10, 15
	s_lshl_b32 s1, s1, 11
	v_add_u32_e32 v198, s1, v0
	global_load_dword v64, v198, s[4:5]
	global_load_dword v128, v198, s[6:7]
	global_load_dword v65, v198, s[4:5] offset:2048
	global_load_dword v129, v198, s[6:7] offset:2048
	v_add_u32_e32 v200, 0x1000, v198
	global_load_dword v66, v200, s[4:5]
	global_load_dword v130, v200, s[6:7]
	global_load_dword v67, v200, s[4:5] offset:2048
	global_load_dword v131, v200, s[6:7] offset:2048
	v_add_u32_e32 v201, 0x2000, v198
	global_load_dword v68, v201, s[4:5]
	global_load_dword v132, v201, s[6:7]
	global_load_dword v69, v201, s[4:5] offset:2048
	global_load_dword v133, v201, s[6:7] offset:2048
	v_add_u32_e32 v199, 0x3000, v198
	global_load_dword v70, v199, s[4:5]
	global_load_dword v134, v199, s[6:7]
	global_load_dword v71, v199, s[4:5] offset:2048
	global_load_dword v135, v199, s[6:7] offset:2048
	v_add_u32_e32 v200, 0x4000, v198
	global_load_dword v72, v200, s[4:5]
	global_load_dword v136, v200, s[6:7]
	global_load_dword v73, v200, s[4:5] offset:2048
	global_load_dword v137, v200, s[6:7] offset:2048
	v_add_u32_e32 v201, 0x5000, v198
	global_load_dword v74, v201, s[4:5]
	global_load_dword v138, v201, s[6:7]
	global_load_dword v75, v201, s[4:5] offset:2048
	global_load_dword v139, v201, s[6:7] offset:2048
	v_add_u32_e32 v199, 0x6000, v198
	global_load_dword v76, v199, s[4:5]
	global_load_dword v140, v199, s[6:7]
	global_load_dword v77, v199, s[4:5] offset:2048
	global_load_dword v141, v199, s[6:7] offset:2048
	v_add_u32_e32 v200, 0x7000, v198
	global_load_dword v78, v200, s[4:5]
	global_load_dword v142, v200, s[6:7]
	s_waitcnt vmcnt(30)
	v_fmac_f32_e32 v165, v6, v96
	v_fmac_f32_e32 v167, v165, v97
	v_fmac_f32_e32 v168, v167, v98
	v_fmac_f32_e32 v169, v168, v99
	v_fmac_f32_e32 v170, v169, v100
	v_fmac_f32_e32 v171, v170, v101
	v_fmac_f32_e32 v172, v171, v102
	v_fmac_f32_e32 v173, v172, v103
	v_fmac_f32_e32 v174, v173, v104
	v_fmac_f32_e32 v175, v174, v105
	v_fmac_f32_e32 v176, v175, v106
	v_fmac_f32_e32 v177, v176, v107
	v_fmac_f32_e32 v178, v177, v108
	v_fmac_f32_e32 v179, v178, v109
	v_fmac_f32_e32 v180, v179, v110
	v_mov_b32_e32 v6, v180
	s_add_i32 s10, s10, 15
	s_branch .Lfp_x
.Lfp_y_last:
	s_waitcnt vmcnt(0)
	v_fmac_f32_e32 v165, v6, v96
	v_fmac_f32_e32 v167, v165, v97
	v_fmac_f32_e32 v168, v167, v98
	v_fmac_f32_e32 v169, v168, v99
	v_fmac_f32_e32 v170, v169, v100
	v_fmac_f32_e32 v171, v170, v101
	v_fmac_f32_e32 v172, v171, v102
	v_fmac_f32_e32 v173, v172, v103
	v_fmac_f32_e32 v174, v173, v104
	v_fmac_f32_e32 v175, v174, v105
	v_fmac_f32_e32 v176, v175, v106
	v_fmac_f32_e32 v177, v176, v107
	v_fmac_f32_e32 v178, v177, v108
	v_fmac_f32_e32 v179, v178, v109
	v_fmac_f32_e32 v180, v179, v110
	v_mov_b32_e32 v6, v180
	s_add_i32 s10, s10, 15
	s_branch .Lfp_done
